# adds: seven no-op lgkmcnt waits in front of the attention QK MFMAs removed (K fragments are already complete at the step barrier)
# baseline (speedup 1.0000x reference)
.LBB0_90:
	s_lshl_b32 s21, s28, 1
	v_add_u32_e32 v213, s21, v225
	ds_read_b64_tr_b16 v[208:209], v213 offset:24576
	ds_read_b64_tr_b16 v[210:211], v213 offset:25088
	v_mfma_f32_32x32x16_bf16 v[128:143], v[204:207], v[172:175], v[64:79]
	v_add_f32_e32 v112, v96, v97
	v_add_f32_e32 v112, v98, v112
	v_add_f32_e32 v112, v99, v112
	v_add_f32_e32 v112, v100, v112
	v_add_f32_e32 v112, v101, v112
	v_cvt_pk_bf16_f32 v164, v96, v97
	v_cvt_pk_bf16_f32 v165, v98, v99
	ds_read_b64_tr_b16 v[204:205], v213 offset:28672
	ds_read_b64_tr_b16 v[206:207], v213 offset:29184
	v_add_f32_e32 v96, v102, v112
	v_mfma_f32_32x32x16_bf16 v[128:143], v[196:199], v[168:171], v[128:143]
	v_add_f32_e32 v96, v103, v96
	v_add_f32_e32 v96, v104, v96
	v_add_f32_e32 v144, v105, v96
	v_cvt_pk_bf16_f32 v166, v100, v101
	v_cvt_pk_bf16_f32 v167, v102, v103
	ds_read_b64_tr_b16 v[96:97], v213 offset:25600
	ds_read_b64_tr_b16 v[98:99], v213 offset:26112
	v_mfma_f32_32x32x16_bf16 v[128:143], v[188:191], v[160:163], v[128:143]
	v_add_f32_e32 v100, v106, v144
	v_add_f32_e32 v100, v107, v100
	v_add_f32_e32 v100, v108, v100
	v_add_f32_e32 v144, v109, v100
	v_cvt_pk_bf16_f32 v156, v104, v105
	v_cvt_pk_bf16_f32 v157, v106, v107
	ds_read_b64_tr_b16 v[100:101], v213 offset:29696
	ds_read_b64_tr_b16 v[102:103], v213 offset:30208
	v_mfma_f32_32x32x16_bf16 v[128:143], v[180:183], v[152:155], v[128:143]
	v_add_f32_e32 v104, v110, v144
	v_add_f32_e32 v104, v111, v104
	v_add_f32_e32 v104, v80, v104
	v_add_f32_e32 v144, v81, v104
	v_cvt_pk_bf16_f32 v158, v108, v109
	v_cvt_pk_bf16_f32 v159, v110, v111
	ds_read_b64_tr_b16 v[104:105], v213 offset:26624
	ds_read_b64_tr_b16 v[106:107], v213 offset:27136
	v_mfma_f32_32x32x16_bf16 v[112:127], v[200:203], v[172:175], v[64:79]
	v_add_f32_e32 v108, v82, v144
	v_add_f32_e32 v108, v83, v108
	v_add_f32_e32 v108, v84, v108
	v_add_f32_e32 v144, v85, v108
	v_cvt_pk_bf16_f32 v148, v80, v81
	v_cvt_pk_bf16_f32 v149, v82, v83
	ds_read_b64_tr_b16 v[108:109], v213 offset:30720
	ds_read_b64_tr_b16 v[110:111], v213 offset:31232
	v_mfma_f32_32x32x16_bf16 v[112:127], v[192:195], v[168:171], v[112:127]
	v_add_f32_e32 v80, v86, v144
	v_add_f32_e32 v80, v87, v80
	v_add_f32_e32 v80, v88, v80
	v_add_f32_e32 v80, v89, v80
	v_cvt_pk_bf16_f32 v150, v84, v85
	v_cvt_pk_bf16_f32 v151, v86, v87
	ds_read_b64_tr_b16 v[84:85], v213 offset:27648
	ds_read_b64_tr_b16 v[86:87], v213 offset:28160
	v_mfma_f32_32x32x16_bf16 v[112:127], v[184:187], v[160:163], v[112:127]
	v_add_f32_e32 v80, v90, v80
	v_add_f32_e32 v80, v91, v80
	v_add_f32_e32 v80, v92, v80
	v_add_f32_e32 v80, v93, v80
	v_cvt_pk_bf16_f32 v144, v88, v89
	v_cvt_pk_bf16_f32 v145, v90, v91
	ds_read_b64_tr_b16 v[88:89], v213 offset:31744
	ds_read_b64_tr_b16 v[90:91], v213 offset:32256
	v_mfma_f32_32x32x16_bf16 v[112:127], v[176:179], v[152:155], v[112:127]
	v_add_f32_e32 v80, v94, v80
	v_add_f32_e32 v80, v95, v80
	v_add_f32_e32 v82, 0, v80
	v_cvt_pk_bf16_f32 v146, v92, v93
	v_cvt_pk_bf16_f32 v147, v94, v95
	v_lshl_add_u64 v[218:219], v[230:231], 0, s[36:37]
	v_lshl_add_u64 v[80:81], v[218:219], 0, s[92:93]
	s_add_i32 s21, s27, s18
	v_lshl_add_u64 v[216:217], v[214:215], 0, s[36:37]
	s_mov_b32 s24, m0
	s_mov_b32 m0, s21
	s_nop 0
	global_load_lds_dwordx4 v[80:81], off
	s_mov_b32 m0, s24
	v_lshl_add_u64 v[80:81], v[216:217], 0, s[0:1]
	s_lshl_b32 s21, s25, 1
	s_add_i32 s21, s21, s19
	s_mov_b32 s24, m0
	s_mov_b32 m0, s21
	s_nop 0
	global_load_lds_dwordx4 v[80:81], off
	s_mov_b32 m0, s24
	v_lshl_add_u64 v[80:81], v[216:217], 0, s[68:69]
	s_addk_i32 s21, 0x2000
	s_mov_b32 s24, m0
	s_mov_b32 m0, s21
	s_nop 0
	global_load_lds_dwordx4 v[80:81], off
	s_mov_b32 m0, s24
	v_max_f32_e32 v80, v129, v129
	v_max_f32_e32 v81, v128, v128
	v_max_f32_e32 v80, v81, v80
	v_max3_f32 v81, v130, v131, v113
	v_max3_f32 v80, v80, v112, v114
	v_max3_f32 v80, v80, v115, v132
	v_max3_f32 v81, v81, v134, v135
	v_max3_f32 v80, v80, v133, v116
	v_max3_f32 v81, v81, v118, v119
	v_max3_f32 v80, v80, v117, v136
	v_max3_f32 v81, v81, v138, v139
	v_max3_f32 v80, v80, v137, v120
	v_max3_f32 v81, v81, v122, v123
	v_max3_f32 v80, v80, v121, v140
	v_max3_f32 v81, v81, v142, v143
	v_max3_f32 v80, v80, v141, v124
	v_max3_f32 v81, v81, v126, v127
	v_max3_f32 v80, v80, v125, v81
	v_mov_b32_e32 v81, v80
	s_nop 1
	v_permlane32_swap_b32_e32 v80, v81
	v_max_f32_e32 v81, v81, v81
	v_max_f32_e32 v80, v80, v80
	v_max_f32_e32 v80, v80, v81
	v_cmp_lt_f32_e32 vcc, s74, v80
	s_cmp_lg_u64 vcc, 0
	v_add_f32_e32 v227, v227, v82
	s_cselect_b64 s[38:39], -1, 0
	s_cbranch_vccnz .LBB0_98
